# v23_qhoist
# baseline (speedup 1.0000x reference)
; __device__ void attn_item(const Params& p, int id) {
;     ...
;     for (int k = 0; k < 8; ++k) *(u32x4*)(KL + (8 * kb + k) * 136 + c8 * 8) = kr[k];
;     transpose8x8(vr, vo);
; #pragma unroll
;     for (int j = 0; j < 8; ++j) *(u32x4*)(VT + (c8 * 8 + j) * 264 + ((kb ^ (c8 & 7)) << 3)) = vo[j];
;   }
;   const int uq = u0 + 16 * w + fr;
;   const int tokq = start + r + d * uq;
;   bf16x8 qf[4];
; #pragma unroll
;   for (int ks = 0; ks < 4; ++ks) qf[ks] = *(const bf16x8*)(base + (size_t)tokq * NP + 32 * ks + 8 * fq);
;   __syncthreads();
;   f32x4 s[9];
; #pragma unroll
;   for (int a = 0; a < 9; ++a) {
;     s[a] = f32x4{0.f, 0.f, 0.f, 0.f};
; #pragma unroll
;     for (int ks = 0; ks < 4; ++ks) {
;       bf16x8 kf = *(const bf16x8*)(KL + (16 * w + 16 * a + fr) * 136 + 32 * ks + 8 * fq);
;       s[a] = __builtin_amdgcn_mfma_f32_16x16x32_bf16(kf, qf[ks], s[a], 0, 0, 0);
;     }
;   }
.LBB0_472:
	s_or_b64 exec, exec, s[4:5]
	v_ashrrev_i32_e32 v116, 2, v79
	v_and_b32_e32 v117, -16, v116
	v_add_u32_e32 v116, s7, v117
	v_or_b32_e32 v116, v116, v80
	v_lshlrev_b32_e32 v116, s6, v116
	v_add_u32_e32 v118, s58, v116
	v_ashrrev_i32_e32 v119, 31, v118
	v_bfe_u32 v120, v79, 4, 2
	v_lshlrev_b64 v[118:119], 15, v[118:119]
	v_lshl_add_u64 v[118:119], s[0:1], 0, v[118:119]
	v_lshlrev_b32_e32 v120, 4, v120
	v_mov_b32_e32 v121, 0
	v_lshl_add_u64 v[118:119], v[118:119], 0, v[120:121]
	global_load_dwordx4 v[124:127], v[118:119], off
	global_load_dwordx4 v[128:131], v[118:119], off offset:64
	global_load_dwordx4 v[132:135], v[118:119], off offset:128
	global_load_dwordx4 v[136:139], v[118:119], off offset:192
	v_mul_lo_u32 v64, v81, s11
	v_lshl_add_u32 v64, v80, 4, v64
	s_waitcnt vmcnt(5)
	ds_write_b128 v64, v[16:19]
	ds_write_b128 v64, v[28:31] offset:272
	ds_write_b128 v64, v[32:35] offset:544
	ds_write_b128 v64, v[44:47] offset:816
	ds_write_b128 v64, v[48:51] offset:1088
	ds_write_b128 v64, v[52:55] offset:1360
	ds_write_b128 v64, v[56:59] offset:1632
	ds_write_b128 v64, v[60:63] offset:1904
	s_waitcnt vmcnt(4)
	v_and_b32_e32 v16, 0xffff, v4
	v_lshrrev_b32_e32 v4, 16, v4
	v_and_or_b32 v44, v0, s15, v4
	v_ashrrev_i32_e32 v4, 2, v79
	v_and_b32_e32 v30, -16, v4
	v_add_u32_e32 v4, s7, v30
	v_or_b32_e32 v32, v4, v80
	v_lshlrev_b32_e32 v4, s6, v32
	v_add_u32_e32 v28, s58, v4
	v_ashrrev_i32_e32 v29, 31, v28
	v_bfe_u32 v66, v79, 4, 2
	v_lshlrev_b64 v[34:35], 15, v[28:29]
	v_lshl_add_u64 v[34:35], s[0:1], 0, v[34:35]
	v_lshlrev_b32_e32 v98, 4, v66
	v_mov_b32_e32 v99, v65
	v_lshl_add_u64 v[82:83], v[34:35], 0, v[98:99]
	v_lshl_or_b32 v16, v0, 16, v16
	v_lshrrev_b32_e32 v0, 16, v12
	v_and_or_b32 v45, v8, s15, v0
	v_lshrrev_b32_e32 v0, 16, v24
	v_and_or_b32 v46, v20, s15, v0
	v_lshrrev_b32_e32 v0, 16, v40
	v_and_or_b32 v47, v36, s15, v0
	v_and_b32_e32 v0, 0xffff, v5
	v_lshl_or_b32 v52, v1, 16, v0
	v_and_b32_e32 v0, 0xffff, v13
	v_lshl_or_b32 v53, v9, 16, v0
	v_and_b32_e32 v0, 0xffff, v25
	v_lshl_or_b32 v54, v21, 16, v0
	v_and_b32_e32 v0, 0xffff, v41
	v_lshl_or_b32 v55, v37, 16, v0
	v_lshrrev_b32_e32 v0, 16, v5
	v_and_or_b32 v34, v1, s15, v0
	v_lshrrev_b32_e32 v0, 16, v13
	v_and_b32_e32 v19, 0xffff, v40
	v_and_or_b32 v35, v9, s15, v0
	v_lshrrev_b32_e32 v0, 16, v25
	v_lshl_or_b32 v19, v36, 16, v19
	v_and_or_b32 v36, v21, s15, v0
	v_lshrrev_b32_e32 v0, 16, v41
	v_and_or_b32 v37, v37, s15, v0
	v_and_b32_e32 v0, 0xffff, v6
	v_lshl_or_b32 v86, v2, 16, v0
	v_and_b32_e32 v0, 0xffff, v14
	v_lshl_or_b32 v87, v10, 16, v0
	v_and_b32_e32 v0, 0xffff, v26
	v_lshl_or_b32 v88, v22, 16, v0
	v_and_b32_e32 v0, 0xffff, v42
	v_lshl_or_b32 v89, v38, 16, v0
	v_lshrrev_b32_e32 v0, 16, v6
	v_and_or_b32 v90, v2, s15, v0
	v_lshrrev_b32_e32 v0, 16, v14
	v_and_or_b32 v91, v10, s15, v0
	v_lshrrev_b32_e32 v0, 16, v26
	v_and_or_b32 v92, v22, s15, v0
	v_lshrrev_b32_e32 v0, 16, v42
	v_and_or_b32 v93, v38, s15, v0
	v_and_b32_e32 v0, 0xffff, v7
	v_lshl_or_b32 v94, v3, 16, v0
	v_and_b32_e32 v0, 0xffff, v15
	v_lshl_or_b32 v95, v11, 16, v0
	v_and_b32_e32 v0, 0xffff, v27
	v_lshl_or_b32 v96, v23, 16, v0
	v_and_b32_e32 v0, 0xffff, v43
	v_bitop3_b32 v4, v81, v79, 7 bitop3:0x78
	v_and_b32_e32 v17, 0xffff, v12
	v_and_b32_e32 v18, 0xffff, v24
	v_lshl_or_b32 v97, v39, 16, v0
	v_lshrrev_b32_e32 v0, 16, v7
	v_lshlrev_b32_e32 v4, 4, v4
	v_mul_u32_u24_e32 v5, 0x1080, v80
	v_lshl_or_b32 v17, v8, 16, v17
	v_lshl_or_b32 v18, v20, 16, v18
	v_and_or_b32 v0, v3, s15, v0
	v_lshrrev_b32_e32 v1, 16, v15
	v_lshrrev_b32_e32 v2, 16, v27
	v_lshrrev_b32_e32 v3, 16, v43
	v_add3_u32 v4, v4, v5, s16
	v_and_or_b32 v1, v11, s15, v1
	v_and_or_b32 v2, v23, s15, v2
	v_and_or_b32 v3, v39, s15, v3
	ds_write_b128 v4, v[16:19]
	ds_write_b128 v4, v[44:47] offset:528
	ds_write_b128 v4, v[52:55] offset:1056
	ds_write_b128 v4, v[34:37] offset:1584
	ds_write_b128 v4, v[86:89] offset:2112
	ds_write_b128 v4, v[90:93] offset:2640
	ds_write_b128 v4, v[94:97] offset:3168
	ds_write_b128 v4, v[0:3] offset:3696
	v_or_b32_e32 v0, v30, v80
	v_mad_u64_u32 v[34:35], s[0:1], v0, s17, v[98:99]
	s_waitcnt lgkmcnt(0)
	s_barrier
	ds_read_b128 v[0:3], v34
	ds_read_b128 v[4:7], v34 offset:64
	s_waitcnt vmcnt(3) lgkmcnt(1)
	v_mfma_f32_16x16x32_bf16 v[0:3], v[0:3], v[124:127], 0
	ds_read_b128 v[8:11], v34 offset:128
	ds_read_b128 v[12:15], v34 offset:13184
	ds_read_b128 v[16:19], v34 offset:17536
	s_waitcnt vmcnt(2) lgkmcnt(3)
	v_mfma_f32_16x16x32_bf16 v[0:3], v[4:7], v[128:131], v[0:3]
	ds_read_b128 v[4:7], v34 offset:192
	ds_read_b128 v[20:23], v34 offset:21888
	ds_read_b128 v[24:27], v34 offset:26240
	s_waitcnt vmcnt(1) lgkmcnt(5)
	v_mfma_f32_16x16x32_bf16 v[0:3], v[8:11], v[132:135], v[0:3]
	ds_read_b128 v[8:11], v34 offset:4352
	ds_read_b128 v[44:47], v34 offset:30592
	s_add_i32 s1, s47, 1
	s_waitcnt vmcnt(0) lgkmcnt(4)
	v_mfma_f32_16x16x32_bf16 v[36:39], v[4:7], v[136:139], v[0:3]
	v_lshlrev_b32_e32 v31, 2, v66
	v_sub_u32_e32 v35, v31, v80
	v_add_u32_e32 v33, 1, v35
	ds_read_b128 v[0:3], v34 offset:4416
	s_waitcnt lgkmcnt(2)
	v_mfma_f32_16x16x32_bf16 v[4:7], v[8:11], v[124:127], 0
	ds_read_b128 v[8:11], v34 offset:4480
	s_lshl_b32 s0, 1, s6
	v_and_b32_e32 v31, 8, v31
	s_waitcnt lgkmcnt(1)
	v_mfma_f32_16x16x32_bf16 v[0:3], v[0:3], v[128:131], v[4:7]
	s_nop 2
	ds_read_b128 v[4:7], v34 offset:4544
	v_lshlrev_b32_e32 v64, 3, v66
	s_waitcnt lgkmcnt(1)
	v_mfma_f32_16x16x32_bf16 v[0:3], v[8:11], v[132:135], v[0:3]
	ds_read_b128 v[8:11], v34 offset:8704
	s_waitcnt lgkmcnt(1)
	v_mfma_f32_16x16x32_bf16 v[40:43], v[4:7], v[136:139], v[0:3]
	s_nop 4
	ds_read_b128 v[0:3], v34 offset:8768
	s_waitcnt lgkmcnt(1)
; __device__ void attn_item(const Params& p, int id) {
;     ...
; #pragma unroll
;   for (int a = 0; a < 9; ++a) {
;     s[a] = f32x4{0.f, 0.f, 0.f, 0.f};
; #pragma unroll
;     for (int ks = 0; ks < 4; ++ks) {
;       bf16x8 kf = *(const bf16x8*)(KL + (16 * w + 16 * a + fr) * 136 + 32 * ks + 8 * fq);
;       s[a] = __builtin_amdgcn_mfma_f32_16x16x32_bf16(kf, qf[ks], s[a], 0, 0, 0);
;     }
;   }
;   const float slope = exp2f(-(float)(h + 1)) * (float)d;
;   const float scale = 0.08838834764831845f;
;   float mx = -1e30f;
; #pragma unroll
;   for (int a = 0; a < 9; ++a)
; #pragma unroll
;     for (int jj = 0; jj < 4; ++jj) {
;       int delta = 16 * a + 4 * fq + jj - 64 - fr;
;       int uk = uq + delta;
;       int ad = delta < 0 ? -delta : delta;
;       bool valid = (ad <= 64) && (uk >= 0) && (uk < L);
;       float v = valid ? s[a][jj] * scale - slope * (float)ad : -1e30f;
;       s[a][jj] = v;
;       mx = fmaxf(mx, v);
;     }
	v_mfma_f32_16x16x32_bf16 v[4:7], v[8:11], v[124:127], 0
	ds_read_b128 v[8:11], v34 offset:8832
	s_waitcnt lgkmcnt(1)
	v_mfma_f32_16x16x32_bf16 v[0:3], v[0:3], v[128:131], v[4:7]
	s_nop 4
	ds_read_b128 v[4:7], v34 offset:8896
	s_waitcnt lgkmcnt(1)
	v_mfma_f32_16x16x32_bf16 v[0:3], v[8:11], v[132:135], v[0:3]
	ds_read_b128 v[8:11], v34 offset:13056
	s_waitcnt lgkmcnt(1)
	v_mfma_f32_16x16x32_bf16 v[0:3], v[4:7], v[136:139], v[0:3]
	ds_read_b128 v[4:7], v34 offset:13120
	s_waitcnt lgkmcnt(1)
	v_mfma_f32_16x16x32_bf16 v[8:11], v[8:11], v[124:127], 0
	s_waitcnt lgkmcnt(0)
	v_mfma_f32_16x16x32_bf16 v[4:7], v[4:7], v[128:131], v[8:11]
	s_nop 5
	ds_read_b128 v[8:11], v34 offset:13248
	v_mfma_f32_16x16x32_bf16 v[4:7], v[12:15], v[132:135], v[4:7]
	ds_read_b128 v[12:15], v34 offset:17408
	s_waitcnt lgkmcnt(1)
	v_mfma_f32_16x16x32_bf16 v[4:7], v[8:11], v[136:139], v[4:7]
	ds_read_b128 v[8:11], v34 offset:17472
	s_waitcnt lgkmcnt(1)
	v_mfma_f32_16x16x32_bf16 v[12:15], v[12:15], v[124:127], 0
	s_waitcnt lgkmcnt(0)
	v_mfma_f32_16x16x32_bf16 v[8:11], v[8:11], v[128:131], v[12:15]
	s_nop 5
	ds_read_b128 v[12:15], v34 offset:17600
	v_mfma_f32_16x16x32_bf16 v[8:11], v[16:19], v[132:135], v[8:11]
	ds_read_b128 v[16:19], v34 offset:21760
	s_waitcnt lgkmcnt(1)
	v_mfma_f32_16x16x32_bf16 v[8:11], v[12:15], v[136:139], v[8:11]
	ds_read_b128 v[12:15], v34 offset:21824
	s_waitcnt lgkmcnt(1)
	v_mfma_f32_16x16x32_bf16 v[16:19], v[16:19], v[124:127], 0
	s_waitcnt lgkmcnt(0)
	v_mfma_f32_16x16x32_bf16 v[12:15], v[12:15], v[128:131], v[16:19]
	s_nop 5
	ds_read_b128 v[16:19], v34 offset:21952
	v_mfma_f32_16x16x32_bf16 v[12:15], v[20:23], v[132:135], v[12:15]
	ds_read_b128 v[20:23], v34 offset:26112
	s_waitcnt lgkmcnt(1)
	v_mfma_f32_16x16x32_bf16 v[12:15], v[16:19], v[136:139], v[12:15]
	ds_read_b128 v[16:19], v34 offset:26176
	s_waitcnt lgkmcnt(1)
	v_mfma_f32_16x16x32_bf16 v[20:23], v[20:23], v[124:127], 0
	s_waitcnt lgkmcnt(0)
	v_mfma_f32_16x16x32_bf16 v[16:19], v[16:19], v[128:131], v[20:23]
	s_nop 5
	ds_read_b128 v[20:23], v34 offset:26304
	v_mfma_f32_16x16x32_bf16 v[16:19], v[24:27], v[132:135], v[16:19]
	ds_read_b128 v[24:27], v34 offset:30464
	s_waitcnt lgkmcnt(1)
	v_mfma_f32_16x16x32_bf16 v[16:19], v[20:23], v[136:139], v[16:19]
	ds_read_b128 v[20:23], v34 offset:30528
	s_waitcnt lgkmcnt(1)
	v_mfma_f32_16x16x32_bf16 v[24:27], v[24:27], v[124:127], 0
	s_waitcnt lgkmcnt(0)
	v_mfma_f32_16x16x32_bf16 v[20:23], v[20:23], v[128:131], v[24:27]
	s_nop 5
	ds_read_b128 v[24:27], v34 offset:30656
	v_mfma_f32_16x16x32_bf16 v[20:23], v[44:47], v[132:135], v[20:23]
	ds_read_b128 v[44:47], v34 offset:34816
	s_waitcnt lgkmcnt(1)
	v_mfma_f32_16x16x32_bf16 v[20:23], v[24:27], v[136:139], v[20:23]
	ds_read_b128 v[24:27], v34 offset:34880
	s_waitcnt lgkmcnt(1)
	v_mfma_f32_16x16x32_bf16 v[44:47], v[44:47], v[124:127], 0
	ds_read_b128 v[48:51], v34 offset:34944
	s_waitcnt lgkmcnt(1)
	v_mfma_f32_16x16x32_bf16 v[24:27], v[24:27], v[128:131], v[44:47]
	s_nop 4
	ds_read_b128 v[44:47], v34 offset:35008
	s_waitcnt lgkmcnt(1)
	v_mfma_f32_16x16x32_bf16 v[24:27], v[48:51], v[132:135], v[24:27]
	v_add_u32_e32 v48, v35, v32
	v_subrev_u32_e32 v49, 45, v48
	v_subrev_u32_e32 v50, 46, v48
	s_waitcnt lgkmcnt(0)
	v_mfma_f32_16x16x32_bf16 v[44:47], v[44:47], v[136:139], v[24:27]
	s_nop 2
	v_cvt_f32_ubyte0_e32 v24, s1
	v_cmp_lt_f32_e32 vcc, s18, v24
	v_sub_u32_e32 v26, 0, v33
	v_max_i32_e32 v27, v33, v26
	v_cndmask_b32_e32 v25, 0, v69, vcc
	v_sub_f32_e32 v24, v25, v24
	v_exp_f32_e32 v24, v24
	v_cvt_f32_u32_e32 v25, s0
	v_sub_u32_e32 v26, 0, v35
	s_and_b64 s[0:1], vcc, exec
	v_max_i32_e32 v26, v35, v26
	s_cselect_b32 s0, 0xffffffc0, 0
	v_cvt_f32_u32_e32 v26, v26
	v_cvt_f32_u32_e32 v27, v27
	v_ldexp_f32 v24, v24, s0
	v_cmp_lt_i32_e32 vcc, v189, v250
	v_mul_f32_e32 v24, v24, v25
	v_add_u32_e32 v33, v33, v32
	v_cndmask_b32_e32 v25, v249, v189, vcc
	v_lshlrev_b32_e32 v25, 2, v25
	v_pk_mul_f32 v[26:27], v[24:25], v[26:27] op_sel_hi:[0,1]
	v_pk_fma_f32 v[8:9], v[8:9], s[14:15], v[26:27] op_sel_hi:[1,0,1] neg_lo:[0,0,1] neg_hi:[0,0,1]
	v_cmp_gt_u32_e32 vcc, s57, v33
	v_sub_u32_e32 v26, 45, v35
	v_cvt_f32_u32_e32 v27, v26
	v_cndmask_b32_e32 v33, v70, v9, vcc
	v_sub_u32_e32 v9, 46, v35
	v_cvt_f32_u32_e32 v26, v9
	v_cmp_gt_u32_e32 vcc, s57, v48
	s_nop 1
	v_cndmask_b32_e32 v34, v70, v8, vcc
	v_pk_mul_f32 v[8:9], v[24:25], v[26:27] op_sel_hi:[0,1]
	v_pk_fma_f32 v[8:9], v[42:43], s[14:15], v[8:9] op_sel_hi:[1,0,1] neg_lo:[0,0,1] neg_hi:[0,0,1]
	v_cmp_gt_u32_e32 vcc, s57, v49
	v_sub_u32_e32 v26, 47, v35
	v_cvt_f32_u32_e32 v27, v26
	v_cndmask_b32_e32 v42, v70, v9, vcc
	v_sub_u32_e32 v9, 48, v35
	v_cvt_f32_u32_e32 v26, v9
	v_cmp_gt_u32_e32 vcc, s57, v50
	v_subrev_u32_e32 v49, 47, v48
	v_subrev_u32_e32 v50, 48, v48
	v_cndmask_b32_e32 v43, v70, v8, vcc
	v_pk_mul_f32 v[8:9], v[24:25], v[26:27] op_sel_hi:[0,1]
	v_pk_fma_f32 v[8:9], v[40:41], s[14:15], v[8:9] op_sel_hi:[1,0,1] neg_lo:[0,0,1] neg_hi:[0,0,1]
	v_cmp_gt_u32_e32 vcc, s57, v49
	v_sub_u32_e32 v49, 62, v35
	v_subrev_u32_e32 v27, 61, v48
	v_cndmask_b32_e32 v40, v70, v9, vcc
	v_cmp_gt_u32_e32 vcc, s57, v50
	v_subrev_u32_e32 v26, 62, v48
	v_cmp_gt_u32_e64 s[4:5], s57, v27
	v_cndmask_b32_e32 v41, v70, v8, vcc
	v_sub_u32_e32 v8, 61, v35
	v_cmp_gt_u32_e32 vcc, s29, v8
	v_cvt_f32_u32_e32 v9, v8
	v_cvt_f32_u32_e32 v8, v49
	v_cmp_gt_u32_e64 s[0:1], s29, v49
	v_cmp_gt_u32_e64 s[6:7], s57, v26
	s_and_b64 vcc, vcc, s[4:5]
	v_pk_mul_f32 v[8:9], v[24:25], v[8:9] op_sel_hi:[0,1]
	v_pk_fma_f32 v[8:9], v[38:39], s[14:15], v[8:9] op_sel_hi:[1,0,1] neg_lo:[0,0,1] neg_hi:[0,0,1]
	v_sub_u32_e32 v38, 64, v35
	v_cndmask_b32_e32 v49, v70, v9, vcc
	s_and_b64 vcc, s[0:1], s[6:7]
; __device__ void attn_item(const Params& p, int id) {
;     ...
;   for (int a = 0; a < 9; ++a)
; #pragma unroll
;     for (int jj = 0; jj < 4; ++jj) {
;       int delta = 16 * a + 4 * fq + jj - 64 - fr;
;       int uk = uq + delta;
;       int ad = delta < 0 ? -delta : delta;
;       bool valid = (ad <= 64) && (uk >= 0) && (uk < L);
;       float v = valid ? s[a][jj] * scale - slope * (float)ad : -1e30f;
;       s[a][jj] = v;
;       mx = fmaxf(mx, v);
;     }
	v_cndmask_b32_e32 v50, v70, v8, vcc
	v_sub_u32_e32 v8, 63, v35
	v_cmp_gt_u32_e32 vcc, s29, v8
	v_cvt_f32_u32_e32 v9, v8
	v_cvt_f32_u32_e32 v8, v38
	v_subrev_u32_e32 v27, 63, v48
	v_subrev_u32_e32 v26, 64, v48
	v_cmp_gt_u32_e64 s[4:5], s57, v27
	v_pk_mul_f32 v[8:9], v[24:25], v[8:9] op_sel_hi:[0,1]
	v_cmp_gt_u32_e64 s[0:1], s29, v38
	v_cmp_gt_u32_e64 s[6:7], s57, v26
	v_pk_fma_f32 v[8:9], v[36:37], s[14:15], v[8:9] op_sel_hi:[1,0,1] neg_lo:[0,0,1] neg_hi:[0,0,1]
	s_and_b64 vcc, vcc, s[4:5]
	v_cndmask_b32_e32 v51, v70, v9, vcc
	s_and_b64 vcc, s[0:1], s[6:7]
	v_cndmask_b32_e32 v52, v70, v8, vcc
	v_max3_f32 v8, v52, s19, v51
	v_max3_f32 v8, v8, v50, v49
	v_max3_f32 v8, v8, v41, v40
	v_max3_f32 v53, v8, v43, v42
	v_add_u32_e32 v8, 0x43, v35
	v_add_u32_e32 v26, 0x42, v35
	v_add_u32_e32 v36, v8, v32
	v_cmp_gt_u32_e32 vcc, s29, v8
	v_cvt_f32_u32_e32 v9, v8
	v_cvt_f32_u32_e32 v8, v26
	v_add_u32_e32 v27, v26, v32
	v_cmp_gt_u32_e64 s[4:5], s57, v36
	v_cmp_gt_u32_e64 s[0:1], s29, v26
	v_pk_mul_f32 v[8:9], v[24:25], v[8:9] op_sel_hi:[0,1]
	v_cmp_gt_u32_e64 s[6:7], s57, v27
	v_pk_fma_f32 v[26:27], v[46:47], s[14:15], v[8:9] op_sel_hi:[1,0,1] neg_lo:[0,0,1] neg_hi:[0,0,1]
	s_and_b64 vcc, vcc, s[4:5]
	v_cndmask_b32_e32 v8, v70, v27, vcc
	s_and_b64 vcc, s[0:1], s[6:7]
	v_cndmask_b32_e32 v9, v70, v26, vcc
	v_add_u32_e32 v26, 0x41, v35
	v_add_u32_e32 v36, 64, v35
	v_add_u32_e32 v38, v26, v32
	v_cvt_f32_u32_e32 v27, v26
	v_cvt_f32_u32_e32 v26, v36
	v_add_u32_e32 v37, v36, v32
	v_cmp_lt_u32_e32 vcc, s30, v35
	v_cmp_gt_u32_e64 s[4:5], s57, v38
	v_pk_mul_f32 v[26:27], v[24:25], v[26:27] op_sel_hi:[0,1]
	v_cmp_gt_u32_e64 s[0:1], s29, v36
	v_cmp_gt_u32_e64 s[6:7], s57, v37
	v_pk_fma_f32 v[36:37], v[44:45], s[14:15], v[26:27] op_sel_hi:[1,0,1] neg_lo:[0,0,1] neg_hi:[0,0,1]
	s_and_b64 vcc, vcc, s[4:5]
	v_cndmask_b32_e32 v26, v70, v37, vcc
	v_add_u32_e32 v37, 50, v35
	v_add_u32_e32 v44, 51, v35
	v_cvt_f32_u32_e32 v39, v44
	v_cvt_f32_u32_e32 v38, v37
	s_and_b64 vcc, s[0:1], s[6:7]
	v_cndmask_b32_e32 v27, v70, v36, vcc
	v_add_u32_e32 v44, v44, v32
	v_add_u32_e32 v45, v37, v32
	v_pk_mul_f32 v[36:37], v[24:25], v[38:39] op_sel_hi:[0,1]
	v_pk_fma_f32 v[36:37], v[22:23], s[14:15], v[36:37] op_sel_hi:[1,0,1] neg_lo:[0,0,1] neg_hi:[0,0,1]
	v_cmp_gt_u32_e32 vcc, s57, v44
	v_add_u32_e32 v44, 49, v35
	v_cvt_f32_u32_e32 v39, v44
	v_cndmask_b32_e32 v22, v70, v37, vcc
	v_add_u32_e32 v37, 48, v35
	v_cvt_f32_u32_e32 v38, v37
	v_cmp_gt_u32_e32 vcc, s57, v45
	v_add_u32_e32 v45, v37, v32
	v_add_u32_e32 v44, v44, v32
	v_cndmask_b32_e32 v23, v70, v36, vcc
	v_pk_mul_f32 v[36:37], v[24:25], v[38:39] op_sel_hi:[0,1]
	v_add_u32_e32 v38, 34, v35
	v_add_u32_e32 v39, 35, v35
	v_pk_fma_f32 v[20:21], v[20:21], s[14:15], v[36:37] op_sel_hi:[1,0,1] neg_lo:[0,0,1] neg_hi:[0,0,1]
	v_cvt_f32_u32_e32 v37, v39
	v_cvt_f32_u32_e32 v36, v38
	v_cmp_gt_u32_e32 vcc, s57, v44
	v_add_u32_e32 v39, v39, v32
	v_add_u32_e32 v44, 33, v35
	v_cndmask_b32_e32 v21, v70, v21, vcc
	v_cmp_gt_u32_e32 vcc, s57, v45
	v_pk_mul_f32 v[36:37], v[24:25], v[36:37] op_sel_hi:[0,1]
	v_pk_fma_f32 v[18:19], v[18:19], s[14:15], v[36:37] op_sel_hi:[1,0,1] neg_lo:[0,0,1] neg_hi:[0,0,1]
	v_cndmask_b32_e32 v20, v70, v20, vcc
	v_cmp_gt_u32_e32 vcc, s57, v39
	v_add_u32_e32 v39, 32, v35
	v_cvt_f32_u32_e32 v37, v44
	v_cvt_f32_u32_e32 v36, v39
	v_add_u32_e32 v38, v38, v32
	v_cndmask_b32_e32 v19, v70, v19, vcc
	v_cmp_gt_u32_e32 vcc, s57, v38
	v_add_u32_e32 v38, v44, v32
	v_pk_mul_f32 v[36:37], v[24:25], v[36:37] op_sel_hi:[0,1]
	v_cndmask_b32_e32 v18, v70, v18, vcc
	v_pk_fma_f32 v[16:17], v[16:17], s[14:15], v[36:37] op_sel_hi:[1,0,1] neg_lo:[0,0,1] neg_hi:[0,0,1]
	v_cmp_gt_u32_e32 vcc, s57, v38
	v_add_u32_e32 v44, 19, v35
	v_cvt_f32_u32_e32 v37, v44
	v_cndmask_b32_e32 v38, v70, v17, vcc
	v_add_u32_e32 v17, 18, v35
	v_cvt_f32_u32_e32 v36, v17
	v_add_u32_e32 v39, v39, v32
	v_cmp_gt_u32_e32 vcc, s57, v39
	v_add_u32_e32 v44, v44, v32
	v_add_u32_e32 v45, v17, v32
	v_cndmask_b32_e32 v39, v70, v16, vcc
	v_pk_mul_f32 v[16:17], v[24:25], v[36:37] op_sel_hi:[0,1]
	v_pk_fma_f32 v[14:15], v[14:15], s[14:15], v[16:17] op_sel_hi:[1,0,1] neg_lo:[0,0,1] neg_hi:[0,0,1]
	v_cmp_gt_u32_e32 vcc, s57, v44
	v_add_u32_e32 v37, 17, v35
	v_cvt_f32_u32_e32 v17, v37
	v_cndmask_b32_e32 v36, v70, v15, vcc
	v_add_u32_e32 v15, 16, v35
	v_cvt_f32_u32_e32 v16, v15
	v_cmp_gt_u32_e32 vcc, s57, v45
	v_add_u32_e32 v37, v37, v32
	v_add_u32_e32 v45, v15, v32
	v_cndmask_b32_e32 v44, v70, v14, vcc
	v_pk_mul_f32 v[14:15], v[24:25], v[16:17] op_sel_hi:[0,1]
	v_pk_fma_f32 v[12:13], v[12:13], s[14:15], v[14:15] op_sel_hi:[1,0,1] neg_lo:[0,0,1] neg_hi:[0,0,1]
	v_cmp_gt_u32_e32 vcc, s57, v37
	v_add_u32_e32 v17, 3, v35
	v_sub_u32_e32 v15, 0, v17
	v_cndmask_b32_e32 v16, v70, v13, vcc
	v_add_u32_e32 v13, 2, v35
	v_sub_u32_e32 v14, 0, v13
	v_max_i32_e32 v14, v13, v14
	v_max_i32_e32 v15, v17, v15
	v_cvt_f32_u32_e32 v15, v15
	v_cvt_f32_u32_e32 v14, v14
	v_cmp_gt_u32_e32 vcc, s57, v45
	v_add_u32_e32 v17, v17, v32
	v_add_u32_e32 v32, v13, v32
	v_cndmask_b32_e32 v37, v70, v12, vcc
	v_pk_mul_f32 v[12:13], v[24:25], v[14:15] op_sel_hi:[0,1]
	v_pk_fma_f32 v[10:11], v[10:11], s[14:15], v[12:13] op_sel_hi:[1,0,1] neg_lo:[0,0,1] neg_hi:[0,0,1]
	v_cmp_gt_u32_e32 vcc, s57, v17
	v_sub_u32_e32 v12, 13, v35
	v_cvt_f32_u32_e32 v13, v12
	v_cndmask_b32_e32 v14, v70, v11, vcc
	v_sub_u32_e32 v11, 14, v35
	v_cvt_f32_u32_e32 v12, v11
	v_cmp_gt_u32_e32 vcc, s57, v32
	v_add_u32_e32 v17, -13, v48
	v_add_u32_e32 v32, -14, v48
	v_cndmask_b32_e32 v15, v70, v10, vcc
	v_pk_mul_f32 v[10:11], v[24:25], v[12:13] op_sel_hi:[0,1]
	v_pk_fma_f32 v[6:7], v[6:7], s[14:15], v[10:11] op_sel_hi:[1,0,1] neg_lo:[0,0,1] neg_hi:[0,0,1]
; __device__ void attn_item(const Params& p, int id) {
;     ...
;       mx = fmaxf(mx, v);
;     }
;   mx = fmaxf(mx, __shfl_xor(mx, 16));
;   mx = fmaxf(mx, __shfl_xor(mx, 32));
;   float l = 0.f;
; #pragma unroll
;   for (int a = 0; a < 9; ++a)
; #pragma unroll
;     for (int jj = 0; jj < 4; ++jj) {
;       float e = s[a][jj] > -1e29f ? __expf(s[a][jj] - mx) : 0.f;
;       s[a][jj] = e;
;       l += e;
;     }
;   l += __shfl_xor(l, 16);
;   l += __shfl_xor(l, 32);
	v_cmp_gt_u32_e32 vcc, s57, v17
	v_sub_u32_e32 v10, 15, v35
	v_cvt_f32_u32_e32 v11, v10
	v_cndmask_b32_e32 v12, v70, v7, vcc
	v_sub_u32_e32 v7, 16, v35
	v_cvt_f32_u32_e32 v10, v7
	v_cmp_gt_u32_e32 vcc, s57, v32
	v_add_u32_e32 v17, -15, v48
	v_add_u32_e32 v32, -16, v48
	v_cndmask_b32_e32 v13, v70, v6, vcc
	v_pk_mul_f32 v[6:7], v[24:25], v[10:11] op_sel_hi:[0,1]
	v_pk_fma_f32 v[4:5], v[4:5], s[14:15], v[6:7] op_sel_hi:[1,0,1] neg_lo:[0,0,1] neg_hi:[0,0,1]
	v_cmp_gt_u32_e32 vcc, s57, v17
	v_sub_u32_e32 v6, 29, v35
	v_cvt_f32_u32_e32 v7, v6
	v_cndmask_b32_e32 v10, v70, v5, vcc
	v_sub_u32_e32 v5, 30, v35
	v_cvt_f32_u32_e32 v6, v5
	v_cmp_gt_u32_e32 vcc, s57, v32
	v_subrev_u32_e32 v17, 29, v48
	v_subrev_u32_e32 v32, 30, v48
	v_cndmask_b32_e32 v11, v70, v4, vcc
	v_pk_mul_f32 v[4:5], v[24:25], v[6:7] op_sel_hi:[0,1]
	v_pk_fma_f32 v[2:3], v[2:3], s[14:15], v[4:5] op_sel_hi:[1,0,1] neg_lo:[0,0,1] neg_hi:[0,0,1]
	v_cmp_gt_u32_e32 vcc, s57, v17
	v_sub_u32_e32 v4, 31, v35
	v_cvt_f32_u32_e32 v5, v4
	v_cndmask_b32_e32 v6, v70, v3, vcc
	v_sub_u32_e32 v3, 32, v35
	v_cvt_f32_u32_e32 v4, v3
	v_cmp_gt_u32_e32 vcc, s57, v32
	v_subrev_u32_e32 v17, 31, v48
	v_subrev_u32_e32 v32, 32, v48
	v_cndmask_b32_e32 v7, v70, v2, vcc
	v_pk_mul_f32 v[2:3], v[24:25], v[4:5] op_sel_hi:[0,1]
	v_pk_fma_f32 v[0:1], v[0:1], s[14:15], v[2:3] op_sel_hi:[1,0,1] neg_lo:[0,0,1] neg_hi:[0,0,1]
	v_cmp_gt_u32_e32 vcc, s57, v17
	s_nop 1
	v_cndmask_b32_e32 v1, v70, v1, vcc
	v_cmp_gt_u32_e32 vcc, s57, v32
	s_nop 1
	v_cndmask_b32_e32 v3, v70, v0, vcc
	v_max3_f32 v0, v53, v3, v1
	v_max3_f32 v0, v0, v7, v6
	v_max3_f32 v0, v0, v11, v10
	v_max3_f32 v0, v0, v13, v12
	v_max3_f32 v0, v0, v34, v33
	v_max3_f32 v0, v0, v15, v14
	v_max3_f32 v0, v0, v37, v16
	v_max3_f32 v0, v0, v44, v36
	v_max3_f32 v0, v0, v39, v38
	v_max3_f32 v0, v0, v18, v19
	v_max3_f32 v0, v0, v20, v21
	v_max3_f32 v0, v0, v23, v22
	v_max3_f32 v0, v0, v27, v26
	v_max3_f32 v2, v0, v9, v8
	ds_bpermute_b32 v4, v25, v2
	v_cmp_lt_i32_e32 vcc, v251, v250
	s_waitcnt lgkmcnt(0)
	v_max_f32_e32 v4, v4, v4
	v_cndmask_b32_e32 v0, v249, v251, vcc
	v_lshlrev_b32_e32 v0, 2, v0
	v_max_f32_e32 v2, v2, v4
	ds_bpermute_b32 v4, v0, v2
	v_cmp_lt_f32_e32 vcc, s28, v51
	s_waitcnt lgkmcnt(0)
	v_max_f32_e32 v4, v4, v4
	v_max_f32_e32 v2, v2, v4
	v_sub_f32_e32 v5, v51, v2
	v_sub_f32_e32 v4, v52, v2
	v_mul_f32_e32 v5, 0x3fb8aa3b, v5
	v_exp_f32_e32 v5, v5
	v_mul_f32_e32 v4, 0x3fb8aa3b, v4
	v_sub_f32_e32 v32, v49, v2
	v_exp_f32_e32 v4, v4
	v_sub_f32_e32 v17, v50, v2
	v_mul_f32_e32 v32, 0x3fb8aa3b, v32
	v_exp_f32_e32 v32, v32
	v_mul_f32_e32 v17, 0x3fb8aa3b, v17
	v_exp_f32_e32 v17, v17
	v_cndmask_b32_e32 v5, 0, v5, vcc
	v_cmp_lt_f32_e32 vcc, s28, v52
	s_nop 1
	v_cndmask_b32_e32 v24, 0, v4, vcc
	v_cmp_lt_f32_e32 vcc, s28, v49
	v_add_f32_e32 v4, 0, v24
	v_add_f32_e32 v4, v5, v4
	v_cndmask_b32_e32 v35, 0, v32, vcc
	v_cmp_lt_f32_e32 vcc, s28, v50
	v_sub_f32_e32 v32, v40, v2
	v_mul_f32_e32 v32, 0x3fb8aa3b, v32
	v_cndmask_b32_e32 v45, 0, v17, vcc
	v_sub_f32_e32 v17, v41, v2
	v_exp_f32_e32 v32, v32
	v_mul_f32_e32 v17, 0x3fb8aa3b, v17
	v_exp_f32_e32 v17, v17
	v_cmp_lt_f32_e32 vcc, s28, v40
	v_add_f32_e32 v4, v45, v4
	v_add_f32_e32 v4, v35, v4
	v_cndmask_b32_e32 v40, 0, v32, vcc
	v_cmp_lt_f32_e32 vcc, s28, v41
	v_sub_f32_e32 v32, v42, v2
	v_mul_f32_e32 v32, 0x3fb8aa3b, v32
	v_cndmask_b32_e32 v41, 0, v17, vcc
	v_sub_f32_e32 v17, v43, v2
	v_exp_f32_e32 v32, v32
	v_mul_f32_e32 v17, 0x3fb8aa3b, v17
	v_exp_f32_e32 v17, v17
	v_cmp_lt_f32_e32 vcc, s28, v42
	v_add_f32_e32 v4, v41, v4
	v_add_f32_e32 v4, v40, v4
	v_cndmask_b32_e32 v42, 0, v32, vcc
	v_cmp_lt_f32_e32 vcc, s28, v43
	v_sub_f32_e32 v32, v1, v2
	v_mul_f32_e32 v32, 0x3fb8aa3b, v32
	v_cndmask_b32_e32 v43, 0, v17, vcc
	v_sub_f32_e32 v17, v3, v2
	v_exp_f32_e32 v32, v32
	v_mul_f32_e32 v17, 0x3fb8aa3b, v17
	v_exp_f32_e32 v17, v17
	v_cmp_lt_f32_e32 vcc, s28, v1
	v_add_f32_e32 v4, v43, v4
	v_add_f32_e32 v4, v42, v4
	v_cndmask_b32_e32 v67, 0, v32, vcc
	v_cmp_lt_f32_e32 vcc, s28, v3
	v_sub_f32_e32 v3, v7, v2
	v_mul_f32_e32 v3, 0x3fb8aa3b, v3
	v_cndmask_b32_e32 v84, 0, v17, vcc
	v_add_f32_e32 v1, v84, v4
	v_sub_f32_e32 v4, v6, v2
	v_mul_f32_e32 v4, 0x3fb8aa3b, v4
	v_exp_f32_e32 v4, v4
	v_exp_f32_e32 v3, v3
	v_cmp_lt_f32_e32 vcc, s28, v6
	v_add_f32_e32 v1, v67, v1
	v_cvt_pk_bf16_f32 v32, v24, v5
	v_cndmask_b32_e32 v85, 0, v4, vcc
	v_cmp_lt_f32_e32 vcc, s28, v7
	v_sub_f32_e32 v4, v10, v2
	v_mul_f32_e32 v4, 0x3fb8aa3b, v4
	v_cndmask_b32_e32 v86, 0, v3, vcc
	v_sub_f32_e32 v3, v11, v2
	v_exp_f32_e32 v4, v4
	v_mul_f32_e32 v3, 0x3fb8aa3b, v3
	v_exp_f32_e32 v3, v3
	v_cmp_lt_f32_e32 vcc, s28, v10
	v_add_f32_e32 v1, v86, v1
	v_add_f32_e32 v1, v85, v1
	v_cndmask_b32_e32 v92, 0, v4, vcc
	v_cmp_lt_f32_e32 vcc, s28, v11
	v_sub_f32_e32 v4, v12, v2
	v_mul_f32_e32 v4, 0x3fb8aa3b, v4
	v_cndmask_b32_e32 v93, 0, v3, vcc
	v_sub_f32_e32 v3, v13, v2
	v_exp_f32_e32 v4, v4
	v_mul_f32_e32 v3, 0x3fb8aa3b, v3
	v_exp_f32_e32 v3, v3
	v_cmp_lt_f32_e32 vcc, s28, v12
	v_add_f32_e32 v1, v93, v1
	v_add_f32_e32 v1, v92, v1
	v_cndmask_b32_e32 v94, 0, v4, vcc
	v_cmp_lt_f32_e32 vcc, s28, v13
	v_sub_f32_e32 v4, v33, v2
	v_mul_f32_e32 v4, 0x3fb8aa3b, v4
	v_cndmask_b32_e32 v95, 0, v3, vcc
	v_sub_f32_e32 v3, v34, v2
	v_exp_f32_e32 v4, v4
	v_mul_f32_e32 v3, 0x3fb8aa3b, v3
	v_exp_f32_e32 v3, v3
	v_cmp_lt_f32_e32 vcc, s28, v33
	v_add_f32_e32 v1, v95, v1
	v_add_f32_e32 v1, v94, v1
	v_cndmask_b32_e32 v104, 0, v4, vcc
	v_cmp_lt_f32_e32 vcc, s28, v34
	v_sub_f32_e32 v4, v14, v2
	v_mul_f32_e32 v4, 0x3fb8aa3b, v4
	v_cndmask_b32_e32 v105, 0, v3, vcc
	v_sub_f32_e32 v3, v15, v2
	v_exp_f32_e32 v4, v4
	v_mul_f32_e32 v3, 0x3fb8aa3b, v3
	v_exp_f32_e32 v3, v3
	v_cmp_lt_f32_e32 vcc, s28, v14
; __device__ void attn_item(const Params& p, int id) {
;     ...
; #pragma unroll
;   for (int a = 0; a < 9; ++a)
; #pragma unroll
;     for (int jj = 0; jj < 4; ++jj) {
;       float e = s[a][jj] > -1e29f ? __expf(s[a][jj] - mx) : 0.f;
;       s[a][jj] = e;
;       l += e;
;     }
;   l += __shfl_xor(l, 16);
;   l += __shfl_xor(l, 32);
;   f32x4 o[8];
; #pragma unroll
;   for (int ct = 0; ct < 8; ++ct) o[ct] = f32x4{0.f, 0.f, 0.f, 0.f};
; #pragma unroll
;   for (int s2 = 0; s2 < 5; ++s2) {
;     const int a0 = 2 * s2, a1 = (s2 < 4) ? 2 * s2 + 1 : 2 * s2;
;     u32x4 pw;
;     pw[0] = pack2(s[a0][0], s[a0][1]);
;     pw[1] = pack2(s[a0][2], s[a0][3]);
;     if (s2 < 4) { pw[2] = pack2(s[a1][0], s[a1][1]); pw[3] = pack2(s[a1][2], s[a1][3]); }
;     else { pw[2] = 0u; pw[3] = 0u; }
;     bf16x8 pf = __builtin_bit_cast(bf16x8, pw);
;     const int key0 = 16 * w + 16 * a0 + 4 * fq, key1 = 16 * w + 16 * a1 + 4 * fq;
; #pragma unroll
;     for (int ct = 0; ct < 8; ++ct) {
;       const int c = 16 * ct + fr;
;       const int sw = (c >> 3) & 7;
;       u32x2 lo = *(const u32x2*)(VT + c * 264 + ((((key0 >> 3) ^ sw) << 3) | (key0 & 7)));
;       u32x2 hi = *(const u32x2*)(VT + c * 264 + ((((key1 >> 3) ^ sw) << 3) | (key1 & 7)));
;       u32x4 vw = {lo[0], lo[1], hi[0], hi[1]};
;       o[ct] = __builtin_amdgcn_mfma_f32_16x16x32_bf16(__builtin_bit_cast(bf16x8, vw), pf, o[ct], 0, 0, 0);
;     }
	v_add_f32_e32 v1, v105, v1
	v_add_f32_e32 v1, v104, v1
	v_cndmask_b32_e32 v106, 0, v4, vcc
	v_cmp_lt_f32_e32 vcc, s28, v15
	v_sub_f32_e32 v4, v16, v2
	v_mul_f32_e32 v4, 0x3fb8aa3b, v4
	v_cndmask_b32_e32 v107, 0, v3, vcc
	v_sub_f32_e32 v3, v37, v2
	v_exp_f32_e32 v4, v4
	v_mul_f32_e32 v3, 0x3fb8aa3b, v3
	v_exp_f32_e32 v3, v3
	v_cmp_lt_f32_e32 vcc, s28, v16
	v_add_f32_e32 v1, v107, v1
	v_add_f32_e32 v1, v106, v1
	v_cndmask_b32_e32 v108, 0, v4, vcc
	v_cmp_lt_f32_e32 vcc, s28, v37
	v_sub_f32_e32 v4, v36, v2
	v_mul_f32_e32 v4, 0x3fb8aa3b, v4
	v_cndmask_b32_e32 v109, 0, v3, vcc
	v_sub_f32_e32 v3, v44, v2
	v_exp_f32_e32 v4, v4
	v_mul_f32_e32 v3, 0x3fb8aa3b, v3
	v_exp_f32_e32 v3, v3
	v_cmp_lt_f32_e32 vcc, s28, v36
	v_add_f32_e32 v1, v109, v1
	v_add_f32_e32 v1, v108, v1
	v_cndmask_b32_e32 v110, 0, v4, vcc
	v_cmp_lt_f32_e32 vcc, s28, v44
	v_sub_f32_e32 v4, v38, v2
	v_mul_f32_e32 v4, 0x3fb8aa3b, v4
	v_cndmask_b32_e32 v111, 0, v3, vcc
	v_sub_f32_e32 v3, v39, v2
	v_exp_f32_e32 v4, v4
	v_mul_f32_e32 v3, 0x3fb8aa3b, v3
	v_exp_f32_e32 v3, v3
	v_cmp_lt_f32_e32 vcc, s28, v38
	v_add_f32_e32 v1, v111, v1
	v_add_f32_e32 v1, v110, v1
	v_cndmask_b32_e32 v16, 0, v4, vcc
	v_cmp_lt_f32_e32 vcc, s28, v39
	v_or_b32_e32 v4, v31, v30
	v_add_u32_e32 v24, 16, v4
	v_cndmask_b32_e32 v17, 0, v3, vcc
	v_add_f32_e32 v11, v17, v1
	v_and_b32_e32 v1, 8, v79
	v_mad_u32_u24 v3, v80, s31, v71
	v_bitop3_b32 v1, v31, v1, v30 bitop3:0x36
	v_lshl_add_u32 v5, v1, 1, v3
	v_and_b32_e32 v1, 8, v64
	v_or_b32_e32 v5, v5, v1
	ds_read2st64_b64 v[12:15], v5 offset1:66
	v_bitop3_b32 v5, v24, v79, 8 bitop3:0x78
	v_lshl_add_u32 v5, v5, 1, v3
	v_or_b32_e32 v6, 16, v80
	v_bitop3_b32 v7, v80, 24, 16 bitop3:0xc8
	v_or_b32_e32 v5, v5, v1
	v_bitop3_b32 v7, v31, v7, v30 bitop3:0x36
	v_bitop3_b32 v10, v24, v6, 24 bitop3:0x78
	ds_read2st64_b64 v[36:39], v5 offset1:66
	v_mad_u32_u24 v5, v80, s31, v72
	v_lshlrev_b32_e32 v56, 1, v7
	v_lshlrev_b32_e32 v57, 1, v10
	v_add_u32_e32 v7, v5, v56
	v_add_u32_e32 v10, v5, v57
	v_or_b32_e32 v7, v7, v1
	v_or_b32_e32 v10, v10, v1
	v_cvt_pk_bf16_f32 v33, v45, v35
	v_cvt_pk_bf16_f32 v34, v41, v40
	s_waitcnt lgkmcnt(1)
	v_mov_b32_e32 v40, v12
	ds_read_b64 v[44:45], v7
	ds_read_b64 v[46:47], v10
	v_or_b32_e32 v10, 32, v80
	v_bitop3_b32 v12, v80, 40, 32 bitop3:0xc8
	v_mov_b32_e32 v41, v13
	v_bitop3_b32 v12, v31, v12, v30 bitop3:0x36
	v_bitop3_b32 v13, v24, v10, 40 bitop3:0x78
	v_mad_u32_u24 v7, v80, s31, v73
	v_lshlrev_b32_e32 v60, 1, v12
	v_lshlrev_b32_e32 v61, 1, v13
	v_add_u32_e32 v12, v7, v60
	v_add_u32_e32 v13, v7, v61
	v_or_b32_e32 v12, v12, v1
	v_or_b32_e32 v13, v13, v1
	v_cvt_pk_bf16_f32 v35, v43, v42
	s_waitcnt lgkmcnt(2)
	v_mov_b32_e32 v42, v36
	ds_read_b64 v[48:49], v12
	ds_read_b64 v[50:51], v13
	v_sub_f32_e32 v12, v19, v2
	v_or_b32_e32 v13, 48, v80
	v_bitop3_b32 v36, v80, 56, 48 bitop3:0xc8
	v_mul_f32_e32 v12, 0x3fb8aa3b, v12
	v_bitop3_b32 v30, v31, v36, v30 bitop3:0x36
	v_bitop3_b32 v24, v24, v13, 56 bitop3:0x78
	v_exp_f32_e32 v62, v12
	v_mad_u32_u24 v12, v80, s31, v74
	v_lshlrev_b32_e32 v30, 1, v30
	v_lshlrev_b32_e32 v24, 1, v24
	v_add_u32_e32 v31, v12, v30
	v_add_u32_e32 v36, v12, v24
	v_mov_b32_e32 v43, v37
	v_or_b32_e32 v31, v31, v1
	v_or_b32_e32 v36, v36, v1
	v_mov_b32_e32 v37, v15
	v_mad_u32_u24 v15, v80, s31, v75
	v_add_f32_e32 v87, v16, v11
	v_sub_f32_e32 v11, v18, v2
	ds_read_b64 v[52:53], v31
	ds_read_b64 v[54:55], v36
	v_mov_b32_e32 v36, v14
	v_add_u32_e32 v14, v15, v56
	v_add_u32_e32 v31, v15, v57
	v_mul_f32_e32 v11, 0x3fb8aa3b, v11
	v_or_b32_e32 v14, v14, v1
	v_or_b32_e32 v31, v31, v1
	ds_read_b64 v[56:57], v14
	ds_read_b64 v[58:59], v31
	v_exp_f32_e32 v31, v11
	v_mad_u32_u24 v11, v80, s31, v76
	v_add_u32_e32 v14, v11, v60
	v_cmp_lt_f32_e32 vcc, s28, v19
	v_or_b32_e32 v14, v14, v1
	v_add_u32_e32 v19, v11, v61
	v_cndmask_b32_e32 v112, 0, v62, vcc
	v_or_b32_e32 v19, v19, v1
	ds_read_b64 v[60:61], v14
	ds_read_b64 v[62:63], v19
	v_mad_u32_u24 v14, v80, s31, v77
	v_add_u32_e32 v19, v14, v30
	v_or_b32_e32 v19, v19, v1
	v_add_u32_e32 v24, v14, v24
	v_or_b32_e32 v24, v24, v1
	ds_read_b64 v[80:81], v19
	ds_read_b64 v[82:83], v24
	v_cmp_lt_f32_e32 vcc, s28, v18
	v_mfma_f32_16x16x32_bf16 v[40:43], v[40:43], v[32:35], 0
	v_sub_f32_e32 v19, v20, v2
	v_cndmask_b32_e32 v24, 0, v31, vcc
	v_add_f32_e32 v18, v24, v87
	s_waitcnt lgkmcnt(10)
	v_mfma_f32_16x16x32_bf16 v[44:47], v[44:47], v[32:35], 0
	v_cmp_lt_f32_e32 vcc, s28, v21
	v_mul_f32_e32 v19, 0x3fb8aa3b, v19
	v_exp_f32_e32 v19, v19
	s_waitcnt lgkmcnt(8)
	v_mfma_f32_16x16x32_bf16 v[48:51], v[48:51], v[32:35], 0
	v_add_f32_e32 v18, v112, v18
	s_waitcnt lgkmcnt(6)
	v_mfma_f32_16x16x32_bf16 v[52:55], v[52:55], v[32:35], 0
	v_mfma_f32_16x16x32_bf16 v[36:39], v[36:39], v[32:35], 0
	s_waitcnt lgkmcnt(4)
	v_mfma_f32_16x16x32_bf16 v[56:59], v[56:59], v[32:35], 0
	s_waitcnt lgkmcnt(2)
	v_mfma_f32_16x16x32_bf16 v[60:63], v[60:63], v[32:35], 0
	s_waitcnt lgkmcnt(0)
	v_mfma_f32_16x16x32_bf16 v[30:33], v[80:83], v[32:35], 0
	v_add_u32_e32 v34, 32, v4
	v_cvt_pk_bf16_f32 v80, v84, v67
	v_bitop3_b32 v67, v34, v79, 8 bitop3:0x78
	v_lshl_add_u32 v67, v67, 1, v3
	v_add_u32_e32 v35, 48, v4
	v_or_b32_e32 v67, v67, v1
	v_cvt_pk_bf16_f32 v81, v86, v85
	ds_read2st64_b64 v[84:87], v67 offset1:66
	v_bitop3_b32 v67, v35, v79, 8 bitop3:0x78
	v_lshl_add_u32 v67, v67, 1, v3
	v_or_b32_e32 v67, v67, v1
	ds_read2st64_b64 v[88:91], v67 offset1:66
	v_bitop3_b32 v67, v34, v6, 24 bitop3:0x78
	v_cvt_pk_bf16_f32 v82, v93, v92
	s_waitcnt lgkmcnt(1)
	v_mov_b32_e32 v93, v85
	v_lshlrev_b32_e32 v67, 1, v67
	v_bitop3_b32 v85, v35, v6, 24 bitop3:0x78
	v_mov_b32_e32 v92, v84
	v_add_u32_e32 v84, v5, v67
	v_lshlrev_b32_e32 v85, 1, v85
	v_cvt_pk_bf16_f32 v83, v95, v94
	s_waitcnt lgkmcnt(0)
; __device__ void attn_item(const Params& p, int id) {
;     ...
;   for (int s2 = 0; s2 < 5; ++s2) {
;     const int a0 = 2 * s2, a1 = (s2 < 4) ? 2 * s2 + 1 : 2 * s2;
;     u32x4 pw;
;     pw[0] = pack2(s[a0][0], s[a0][1]);
;     pw[1] = pack2(s[a0][2], s[a0][3]);
;     if (s2 < 4) { pw[2] = pack2(s[a1][0], s[a1][1]); pw[3] = pack2(s[a1][2], s[a1][3]); }
;     else { pw[2] = 0u; pw[3] = 0u; }
;     bf16x8 pf = __builtin_bit_cast(bf16x8, pw);
;     const int key0 = 16 * w + 16 * a0 + 4 * fq, key1 = 16 * w + 16 * a1 + 4 * fq;
; #pragma unroll
;     for (int ct = 0; ct < 8; ++ct) {
;       const int c = 16 * ct + fr;
;       const int sw = (c >> 3) & 7;
;       u32x2 lo = *(const u32x2*)(VT + c * 264 + ((((key0 >> 3) ^ sw) << 3) | (key0 & 7)));
;       u32x2 hi = *(const u32x2*)(VT + c * 264 + ((((key1 >> 3) ^ sw) << 3) | (key1 & 7)));
;       u32x4 vw = {lo[0], lo[1], hi[0], hi[1]};
;       o[ct] = __builtin_amdgcn_mfma_f32_16x16x32_bf16(__builtin_bit_cast(bf16x8, vw), pf, o[ct], 0, 0, 0);
;     }
	v_mov_b32_e32 v94, v88
	v_or_b32_e32 v84, v84, v1
	v_add_u32_e32 v88, v5, v85
	v_or_b32_e32 v88, v88, v1
	ds_read_b64 v[96:97], v84
	ds_read_b64 v[98:99], v88
	v_bitop3_b32 v84, v34, v10, 40 bitop3:0x78
	v_lshlrev_b32_e32 v113, 1, v84
	v_bitop3_b32 v88, v35, v10, 40 bitop3:0x78
	v_add_u32_e32 v84, v7, v113
	v_lshlrev_b32_e32 v114, 1, v88
	v_mov_b32_e32 v95, v89
	v_or_b32_e32 v84, v84, v1
	v_add_u32_e32 v88, v7, v114
	v_or_b32_e32 v88, v88, v1
	ds_read_b64 v[100:101], v84
	ds_read_b64 v[102:103], v88
	v_sub_f32_e32 v84, v21, v2
	v_bitop3_b32 v21, v34, v13, 56 bitop3:0x78
	s_waitcnt lgkmcnt(2)
	v_mfma_f32_16x16x32_bf16 v[44:47], v[96:99], v[80:83], v[44:47]
	v_lshlrev_b32_e32 v96, 1, v21
	v_bitop3_b32 v34, v35, v13, 56 bitop3:0x78
	v_mul_f32_e32 v84, 0x3fb8aa3b, v84
	v_add_u32_e32 v21, v12, v96
	v_lshlrev_b32_e32 v97, 1, v34
	v_exp_f32_e32 v84, v84
	v_or_b32_e32 v21, v21, v1
	v_add_u32_e32 v34, v12, v97
	v_mfma_f32_16x16x32_bf16 v[40:43], v[92:95], v[80:83], v[40:43]
	v_or_b32_e32 v34, v34, v1
	ds_read_b64 v[92:93], v21
	ds_read_b64 v[94:95], v34
	v_mov_b32_e32 v88, v86
	v_mov_b32_e32 v89, v87
	v_cndmask_b32_e32 v115, 0, v84, vcc
	v_add_u32_e32 v21, v15, v67
	v_add_u32_e32 v34, v15, v85
	v_cmp_lt_f32_e32 vcc, s28, v20
	v_or_b32_e32 v21, v21, v1
	v_or_b32_e32 v34, v34, v1
	v_cndmask_b32_e32 v67, 0, v19, vcc
	ds_read_b64 v[84:85], v21
	ds_read_b64 v[86:87], v34
	s_waitcnt lgkmcnt(2)
	v_mfma_f32_16x16x32_bf16 v[52:55], v[92:95], v[80:83], v[52:55]
	v_add_f32_e32 v92, v67, v18
	v_add_u32_e32 v34, v11, v113
	v_add_u32_e32 v35, v11, v114
	v_mfma_f32_16x16x32_bf16 v[18:21], v[88:91], v[80:83], v[36:39]
	v_or_b32_e32 v34, v34, v1
	v_cmp_lt_f32_e32 vcc, s28, v22
	s_nop 0
	v_add_u32_e32 v38, v14, v96
	v_or_b32_e32 v36, v35, v1
	v_or_b32_e32 v38, v38, v1
	v_add_u32_e32 v39, v14, v97
	ds_read_b64 v[34:35], v34
	ds_read_b64 v[36:37], v36
	v_or_b32_e32 v39, v39, v1
	ds_read_b64 v[88:89], v38
	ds_read_b64 v[90:91], v39
	v_sub_f32_e32 v38, v23, v2
	v_mfma_f32_16x16x32_bf16 v[48:51], v[100:103], v[80:83], v[48:51]
	v_mul_f32_e32 v101, 0x3fb8aa3b, v38
	v_sub_f32_e32 v38, v22, v2
	v_mul_f32_e32 v38, 0x3fb8aa3b, v38
	v_add_u32_e32 v103, 64, v4
	v_exp_f32_e32 v102, v38
	v_bitop3_b32 v38, v103, v79, 8 bitop3:0x78
	v_lshl_add_u32 v38, v38, 1, v3
	v_or_b32_e32 v38, v38, v1
	s_waitcnt lgkmcnt(4)
	v_mfma_f32_16x16x32_bf16 v[56:59], v[84:87], v[80:83], v[56:59]
	v_add_f32_e32 v100, v115, v92
	s_waitcnt lgkmcnt(2)
	v_mfma_f32_16x16x32_bf16 v[34:37], v[34:37], v[80:83], v[60:63]
	s_waitcnt lgkmcnt(0)
	v_mfma_f32_16x16x32_bf16 v[30:33], v[88:91], v[80:83], v[30:33]
	s_nop 0
	v_cvt_pk_bf16_f32 v60, v105, v104
	v_add_u32_e32 v104, 0x50, v4
	ds_read2st64_b64 v[80:83], v38 offset1:66
	v_bitop3_b32 v38, v104, v79, 8 bitop3:0x78
	v_lshl_add_u32 v38, v38, 1, v3
	v_or_b32_e32 v38, v38, v1
	ds_read2st64_b64 v[84:87], v38 offset1:66
	v_bitop3_b32 v38, v103, v6, 24 bitop3:0x78
	s_waitcnt lgkmcnt(1)
	v_mov_b32_e32 v88, v80
	v_lshlrev_b32_e32 v80, 1, v38
	v_bitop3_b32 v39, v104, v6, 24 bitop3:0x78
	v_mov_b32_e32 v89, v81
	v_add_u32_e32 v38, v5, v80
	v_lshlrev_b32_e32 v81, 1, v39
	v_or_b32_e32 v38, v38, v1
	v_add_u32_e32 v39, v5, v81
	v_or_b32_e32 v39, v39, v1
	ds_read_b64 v[92:93], v38
	ds_read_b64 v[94:95], v39
	v_bitop3_b32 v38, v103, v10, 40 bitop3:0x78
	v_lshlrev_b32_e32 v105, 1, v38
	v_bitop3_b32 v39, v104, v10, 40 bitop3:0x78
	v_cvt_pk_bf16_f32 v61, v107, v106
	v_add_u32_e32 v38, v7, v105
	v_lshlrev_b32_e32 v106, 1, v39
	v_or_b32_e32 v38, v38, v1
	v_add_u32_e32 v39, v7, v106
	s_waitcnt lgkmcnt(2)
	v_mov_b32_e32 v90, v84
	v_mov_b32_e32 v91, v85
	v_or_b32_e32 v39, v39, v1
	ds_read_b64 v[96:97], v38
	ds_read_b64 v[98:99], v39
	v_cvt_pk_bf16_f32 v62, v109, v108
	v_cvt_pk_bf16_f32 v63, v111, v110
	v_exp_f32_e32 v84, v101
	v_cndmask_b32_e32 v101, 0, v102, vcc
	v_cmp_lt_f32_e32 vcc, s28, v23
	v_bitop3_b32 v23, v103, v13, 56 bitop3:0x78
	v_mfma_f32_16x16x32_bf16 v[38:41], v[88:91], v[60:63], v[40:43]
	v_lshlrev_b32_e32 v23, 1, v23
	v_cndmask_b32_e32 v22, 0, v84, vcc
	v_mov_b32_e32 v84, v82
	s_waitcnt lgkmcnt(2)
	v_mfma_f32_16x16x32_bf16 v[42:45], v[92:95], v[60:63], v[44:47]
	v_mov_b32_e32 v85, v83
	v_add_f32_e32 v100, v22, v100
	v_sub_f32_e32 v93, v26, v2
	s_waitcnt lgkmcnt(0)
	v_mfma_f32_16x16x32_bf16 v[46:49], v[96:99], v[60:63], v[48:51]
	v_add_u32_e32 v97, 0x70, v4
	v_mul_f32_e32 v98, 0x3fb8aa3b, v93
	v_cmp_lt_f32_e32 vcc, s28, v26
	v_bitop3_b32 v51, v104, v13, 56 bitop3:0x78
	v_add_u32_e32 v50, v12, v23
	v_lshlrev_b32_e32 v92, 1, v51
	v_or_b32_e32 v50, v50, v1
	v_add_u32_e32 v51, v12, v92
	v_or_b32_e32 v51, v51, v1
	ds_read_b64 v[88:89], v50
	ds_read_b64 v[90:91], v51
	v_add_u32_e32 v50, v15, v80
	v_or_b32_e32 v50, v50, v1
	v_add_u32_e32 v51, v15, v81
	v_or_b32_e32 v51, v51, v1
	ds_read_b64 v[80:81], v50
	ds_read_b64 v[82:83], v51
	s_waitcnt lgkmcnt(2)
	v_mfma_f32_16x16x32_bf16 v[50:53], v[88:91], v[60:63], v[52:55]
	v_add_u32_e32 v23, v14, v23
	v_or_b32_e32 v23, v23, v1
	s_nop 0
	v_sub_f32_e32 v54, v27, v2
	v_mul_f32_e32 v54, 0x3fb8aa3b, v54
	v_exp_f32_e32 v96, v54
	v_add_u32_e32 v54, v11, v105
	v_add_u32_e32 v55, v11, v106
	v_or_b32_e32 v54, v54, v1
	v_or_b32_e32 v55, v55, v1
	v_mfma_f32_16x16x32_bf16 v[18:21], v[84:87], v[60:63], v[18:21]
	ds_read_b64 v[84:85], v54
	ds_read_b64 v[86:87], v55
	s_waitcnt lgkmcnt(2)
	v_mfma_f32_16x16x32_bf16 v[54:57], v[80:83], v[60:63], v[56:59]
	s_nop 2
	v_add_u32_e32 v58, v14, v92
	v_or_b32_e32 v58, v58, v1
	ds_read_b64 v[80:81], v23
	ds_read_b64 v[82:83], v58
	v_add_u32_e32 v23, 0x60, v4
	v_bitop3_b32 v58, v23, v79, 8 bitop3:0x78
	v_lshl_add_u32 v58, v58, 1, v3
	v_or_b32_e32 v58, v58, v1
	s_waitcnt lgkmcnt(2)
; __device__ void attn_item(const Params& p, int id) {
;     ...
;   l += __shfl_xor(l, 16);
;   l += __shfl_xor(l, 32);
;     ...
;   for (int s2 = 0; s2 < 5; ++s2) {
;     const int a0 = 2 * s2, a1 = (s2 < 4) ? 2 * s2 + 1 : 2 * s2;
;     u32x4 pw;
;     pw[0] = pack2(s[a0][0], s[a0][1]);
;     pw[1] = pack2(s[a0][2], s[a0][3]);
;     if (s2 < 4) { pw[2] = pack2(s[a1][0], s[a1][1]); pw[3] = pack2(s[a1][2], s[a1][3]); }
;     else { pw[2] = 0u; pw[3] = 0u; }
;     bf16x8 pf = __builtin_bit_cast(bf16x8, pw);
;     const int key0 = 16 * w + 16 * a0 + 4 * fq, key1 = 16 * w + 16 * a1 + 4 * fq;
; #pragma unroll
;     for (int ct = 0; ct < 8; ++ct) {
;       const int c = 16 * ct + fr;
;       const int sw = (c >> 3) & 7;
;       u32x2 lo = *(const u32x2*)(VT + c * 264 + ((((key0 >> 3) ^ sw) << 3) | (key0 & 7)));
;       u32x2 hi = *(const u32x2*)(VT + c * 264 + ((((key1 >> 3) ^ sw) << 3) | (key1 & 7)));
;       u32x4 vw = {lo[0], lo[1], hi[0], hi[1]};
;       o[ct] = __builtin_amdgcn_mfma_f32_16x16x32_bf16(__builtin_bit_cast(bf16x8, vw), pf, o[ct], 0, 0, 0);
;     }
	v_mfma_f32_16x16x32_bf16 v[34:37], v[84:87], v[60:63], v[34:37]
	ds_read2st64_b64 v[84:87], v58 offset1:66
	v_bitop3_b32 v58, v97, v79, 8 bitop3:0x78
	v_lshl_add_u32 v58, v58, 1, v3
	v_or_b32_e32 v58, v58, v1
	ds_read2st64_b64 v[88:91], v58 offset1:66
	s_waitcnt lgkmcnt(2)
	v_mfma_f32_16x16x32_bf16 v[30:33], v[80:83], v[60:63], v[30:33]
	s_waitcnt lgkmcnt(1)
	v_mov_b32_e32 v58, v84
	v_mov_b32_e32 v59, v85
	v_cvt_pk_bf16_f32 v80, v17, v16
	s_waitcnt lgkmcnt(0)
	v_mov_b32_e32 v60, v88
	v_mov_b32_e32 v61, v89
	v_bitop3_b32 v16, v23, v6, 24 bitop3:0x78
	v_cvt_pk_bf16_f32 v83, v22, v101
	v_lshlrev_b32_e32 v16, 1, v16
	v_bitop3_b32 v22, v97, v6, 24 bitop3:0x78
	v_add_u32_e32 v17, v5, v16
	v_lshlrev_b32_e32 v22, 1, v22
	v_cvt_pk_bf16_f32 v81, v24, v112
	v_cvt_pk_bf16_f32 v82, v67, v115
	v_or_b32_e32 v17, v17, v1
	v_add_u32_e32 v24, v5, v22
	v_mfma_f32_16x16x32_bf16 v[38:41], v[58:61], v[80:83], v[38:41]
	v_or_b32_e32 v24, v24, v1
	ds_read_b64 v[58:59], v17
	ds_read_b64 v[60:61], v24
	v_bitop3_b32 v17, v23, v10, 40 bitop3:0x78
	v_lshlrev_b32_e32 v24, 1, v17
	v_bitop3_b32 v62, v97, v10, 40 bitop3:0x78
	v_add_u32_e32 v17, v7, v24
	v_lshlrev_b32_e32 v62, 1, v62
	v_or_b32_e32 v17, v17, v1
	v_add_u32_e32 v63, v7, v62
	v_or_b32_e32 v63, v63, v1
	ds_read_b64 v[92:93], v17
	ds_read_b64 v[94:95], v63
	v_bitop3_b32 v17, v23, v13, 56 bitop3:0x78
	v_lshlrev_b32_e32 v63, 1, v17
	v_bitop3_b32 v23, v97, v13, 56 bitop3:0x78
	v_add_u32_e32 v17, v12, v63
	v_lshlrev_b32_e32 v67, 1, v23
	v_add_u32_e32 v16, v15, v16
	v_or_b32_e32 v17, v17, v1
	v_add_u32_e32 v23, v12, v67
	v_or_b32_e32 v16, v16, v1
	v_add_u32_e32 v22, v15, v22
	v_mov_b32_e32 v88, v86
	v_mov_b32_e32 v89, v87
	s_waitcnt lgkmcnt(2)
	v_mfma_f32_16x16x32_bf16 v[42:45], v[58:61], v[80:83], v[42:45]
	v_or_b32_e32 v23, v23, v1
	ds_read_b64 v[58:59], v17
	ds_read_b64 v[60:61], v23
	v_exp_f32_e32 v17, v98
	s_waitcnt lgkmcnt(2)
	v_mfma_f32_16x16x32_bf16 v[46:49], v[92:95], v[80:83], v[46:49]
	v_or_b32_e32 v22, v22, v1
	ds_read_b64 v[92:93], v16
	ds_read_b64 v[94:95], v22
	v_cndmask_b32_e32 v26, 0, v17, vcc
	v_mfma_f32_16x16x32_bf16 v[16:19], v[88:91], v[80:83], v[18:21]
	v_add_u32_e32 v24, v11, v24
	v_or_b32_e32 v24, v24, v1
	v_cmp_lt_f32_e32 vcc, s28, v27
	v_sub_f32_e32 v20, v9, v2
	v_mul_f32_e32 v84, 0x3fb8aa3b, v20
	s_waitcnt lgkmcnt(0)
	v_mfma_f32_16x16x32_bf16 v[20:23], v[92:95], v[80:83], v[54:57]
	v_cndmask_b32_e32 v27, 0, v96, vcc
	v_sub_f32_e32 v85, v8, v2
	v_cmp_lt_f32_e32 vcc, s28, v8
	v_add_u32_e32 v54, v11, v62
	v_or_b32_e32 v56, v54, v1
	ds_read_b64 v[54:55], v24
	ds_read_b64 v[56:57], v56
	v_add_u32_e32 v8, 0x80, v4
	v_bitop3_b32 v4, v8, v79, 8 bitop3:0x78
	v_mfma_f32_16x16x32_bf16 v[50:53], v[58:61], v[80:83], v[50:53]
	v_add_u32_e32 v24, v14, v63
	v_add_u32_e32 v58, v14, v67
	v_lshl_add_u32 v3, v4, 1, v3
	v_or_b32_e32 v24, v24, v1
	v_or_b32_e32 v60, v58, v1
	v_or_b32_e32 v3, v3, v1
	ds_read_b64 v[58:59], v24
	ds_read_b64 v[60:61], v60
	v_mul_f32_e32 v24, 0x3fb8aa3b, v85
	s_waitcnt lgkmcnt(2)
	v_mfma_f32_16x16x32_bf16 v[34:37], v[54:57], v[80:83], v[34:37]
	ds_read2st64_b64 v[54:57], v3 offset1:66
	v_bitop3_b32 v3, v8, v6, 24 bitop3:0x78
	v_bitop3_b32 v6, v8, v10, 40 bitop3:0x78
	v_exp_f32_e32 v24, v24
	v_lshlrev_b32_e32 v63, 1, v6
	v_lshlrev_b32_e32 v3, 1, v3
	v_add_u32_e32 v6, v7, v63
	v_bitop3_b32 v7, v8, v13, 56 bitop3:0x78
	v_exp_f32_e32 v62, v84
	v_add_u32_e32 v4, v5, v3
	v_lshlrev_b32_e32 v67, 1, v7
	v_add_u32_e32 v3, v15, v3
	v_or_b32_e32 v4, v4, v1
	v_or_b32_e32 v6, v6, v1
	v_add_u32_e32 v7, v12, v67
	v_or_b32_e32 v3, v3, v1
	v_cndmask_b32_e32 v24, 0, v24, vcc
	v_cmp_lt_f32_e32 vcc, s28, v9
	ds_read_b64 v[4:5], v4
	v_or_b32_e32 v7, v7, v1
	ds_read_b64 v[84:85], v6
	ds_read_b64 v[88:89], v7
	ds_read_b64 v[8:9], v3
	v_add_f32_e32 v3, v101, v100
	v_add_f32_e32 v3, v27, v3
	v_cndmask_b32_e32 v62, 0, v62, vcc
	v_add_f32_e32 v3, v26, v3
	v_add_f32_e32 v3, v62, v3
	v_add_f32_e32 v3, v24, v3
	s_waitcnt lgkmcnt(5)
	v_mfma_f32_16x16x32_bf16 v[30:33], v[58:61], v[80:83], v[30:33]
	v_cvt_pk_bf16_f32 v58, v27, v26
	ds_bpermute_b32 v26, v25, v3
	v_add_u32_e32 v11, v11, v63
	v_add_u32_e32 v14, v14, v67
	v_or_b32_e32 v11, v11, v1
	v_or_b32_e32 v1, v14, v1
	v_cvt_pk_bf16_f32 v59, v62, v24
	ds_read_b64 v[12:13], v11
	ds_read_b64 v[24:25], v1
	s_waitcnt lgkmcnt(2)
; __device__ void attn_item(const Params& p, int id) {
;     ...
;   const float inv = 1.f / l;
;   u16* og = p.OG + ((size_t)g * NTOK + tokq) * 1024 + h * 128;
; #pragma unroll
;   for (int ct = 0; ct < 8; ++ct) {
;     u32x2 ov;
;     ov[0] = pack2(o[ct][0] * inv, o[ct][1] * inv);
;     ov[1] = pack2(o[ct][2] * inv, o[ct][3] * inv);
;     *(u32x2*)(og + 16 * ct + 4 * fq) = ov;
;   }
;   if (fq == 0) p.LSE[((size_t)g * NTOK + tokq) * 8 + h] = mx + __logf(l);
	v_add_f32_e32 v1, v3, v26
	ds_bpermute_b32 v0, v0, v1
	v_mov_b32_e32 v10, v8
	v_mov_b32_e32 v11, v9
	s_waitcnt lgkmcnt(1)
	v_mov_b32_e32 v26, v24
	v_mov_b32_e32 v27, v25
	s_waitcnt lgkmcnt(0)
	v_add_f32_e32 v3, v1, v0
	v_mov_b32_e32 v60, v65
	v_mov_b32_e32 v61, v65
	v_mov_b32_e32 v6, v4
	v_mov_b32_e32 v7, v5
	v_mfma_f32_16x16x32_bf16 v[8:11], v[8:11], v[58:61], v[20:23]
	v_mov_b32_e32 v86, v84
	v_mov_b32_e32 v87, v85
	v_mov_b32_e32 v90, v88
	v_mfma_f32_16x16x32_bf16 v[20:23], v[24:27], v[58:61], v[30:33]
	v_mov_b32_e32 v91, v89
	v_mfma_f32_16x16x32_bf16 v[4:7], v[4:7], v[58:61], v[42:45]
	s_lshl_b64 s[0:1], s[8:9], 14
	v_mov_b32_e32 v80, v54
	v_mov_b32_e32 v81, v55
	v_mov_b32_e32 v82, v54
	v_mov_b32_e32 v83, v55
	v_mov_b32_e32 v54, v56
	v_mov_b32_e32 v55, v57
	v_rcp_f32_e32 v24, v3
	s_nop 0
	v_lshl_add_u64 v[0:1], s[0:1], 0, v[28:29]
	v_mfma_f32_16x16x32_bf16 v[42:45], v[84:87], v[58:61], v[46:49]
	v_lshlrev_b64 v[26:27], 11, v[0:1]
	v_lshl_add_u64 v[26:27], s[80:81], 0, v[26:27]
	s_lshl_b32 s8, s56, 1
	v_mfma_f32_16x16x32_bf16 v[46:49], v[88:91], v[58:61], v[50:53]
	v_lshl_add_u64 v[26:27], v[26:27], 0, s[8:9]
	v_pk_mul_f32 v[4:5], v[24:25], v[4:5] op_sel_hi:[0,1]
	v_pk_mul_f32 v[6:7], v[24:25], v[6:7] op_sel_hi:[0,1]
	v_mov_b32_e32 v14, v12
	v_mov_b32_e32 v15, v13
	v_lshl_add_u64 v[26:27], v[26:27], 0, v[64:65]
	v_cvt_pk_bf16_f32 v4, v4, v5
	v_cvt_pk_bf16_f32 v5, v6, v7
	v_mfma_f32_16x16x32_bf16 v[16:19], v[54:57], v[58:61], v[16:19]
	global_store_dwordx2 v[26:27], v[4:5], off offset:32
	v_pk_mul_f32 v[4:5], v[24:25], v[42:43] op_sel_hi:[0,1]
	v_pk_mul_f32 v[6:7], v[24:25], v[44:45] op_sel_hi:[0,1]
	v_cvt_pk_bf16_f32 v4, v4, v5
	v_cvt_pk_bf16_f32 v5, v6, v7
	global_store_dwordx2 v[26:27], v[4:5], off offset:64
	v_pk_mul_f32 v[4:5], v[24:25], v[46:47] op_sel_hi:[0,1]
	v_pk_mul_f32 v[6:7], v[24:25], v[48:49] op_sel_hi:[0,1]
	v_cvt_pk_bf16_f32 v4, v4, v5
	v_cvt_pk_bf16_f32 v5, v6, v7
	v_mfma_f32_16x16x32_bf16 v[12:15], v[12:15], v[58:61], v[34:37]
	global_store_dwordx2 v[26:27], v[4:5], off offset:96
	v_pk_mul_f32 v[4:5], v[24:25], v[16:17] op_sel_hi:[0,1]
	v_pk_mul_f32 v[6:7], v[24:25], v[18:19] op_sel_hi:[0,1]
	v_cvt_pk_bf16_f32 v4, v4, v5
	v_cvt_pk_bf16_f32 v5, v6, v7
	v_mfma_f32_16x16x32_bf16 v[38:41], v[80:83], v[58:61], v[38:41]
	global_store_dwordx2 v[26:27], v[4:5], off offset:128
	v_pk_mul_f32 v[4:5], v[24:25], v[8:9] op_sel_hi:[0,1]
	v_pk_mul_f32 v[6:7], v[24:25], v[10:11] op_sel_hi:[0,1]
	v_cvt_pk_bf16_f32 v4, v4, v5
	v_cvt_pk_bf16_f32 v5, v6, v7
	global_store_dwordx2 v[26:27], v[4:5], off offset:160
	v_pk_mul_f32 v[4:5], v[24:25], v[12:13] op_sel_hi:[0,1]
	v_pk_mul_f32 v[6:7], v[24:25], v[14:15] op_sel_hi:[0,1]
	v_cvt_pk_bf16_f32 v4, v4, v5
	v_cvt_pk_bf16_f32 v5, v6, v7
	v_pk_mul_f32 v[28:29], v[24:25], v[38:39] op_sel_hi:[0,1]
	v_pk_mul_f32 v[30:31], v[24:25], v[40:41] op_sel_hi:[0,1]
	global_store_dwordx2 v[26:27], v[4:5], off offset:192
	v_pk_mul_f32 v[4:5], v[24:25], v[20:21] op_sel_hi:[0,1]
	v_pk_mul_f32 v[6:7], v[24:25], v[22:23] op_sel_hi:[0,1]
	v_cvt_pk_bf16_f32 v28, v28, v29
	v_cvt_pk_bf16_f32 v29, v30, v31
	v_cvt_pk_bf16_f32 v4, v4, v5
	v_cvt_pk_bf16_f32 v5, v6, v7
	v_cmp_eq_u32_e32 vcc, 0, v66
	global_store_dwordx2 v[26:27], v[28:29], off
	global_store_dwordx2 v[26:27], v[4:5], off offset:224
	s_and_saveexec_b64 s[4:5], vcc
	s_cbranch_execz .LBB0_449
	v_cmp_gt_f32_e32 vcc, s34, v3
	v_lshlrev_b64 v[0:1], 5, v[0:1]
	v_lshl_add_u64 v[0:1], s[42:43], 0, v[0:1]
	v_cndmask_b32_e64 v4, 0, 32, vcc
	v_ldexp_f32 v3, v3, v4
	v_log_f32_e32 v3, v3
	s_lshl_b32 s8, s47, 2
	v_lshl_add_u64 v[0:1], v[0:1], 0, s[8:9]
	v_mul_f32_e32 v4, 0x3f317217, v3
	v_fma_f32 v4, v3, s35, -v4
	v_fmac_f32_e32 v4, 0x3377d1cf, v3
	v_fmac_f32_e32 v4, 0x3f317217, v3
	v_cmp_lt_f32_e64 s[0:1], |v3|, s46
	s_nop 1
	v_cndmask_b32_e64 v3, v3, v4, s[0:1]
	v_cndmask_b32_e32 v4, 0, v78, vcc
	v_sub_f32_e32 v3, v3, v4
	v_add_f32_e32 v2, v2, v3
	global_store_dword v[0:1], v2, off
	s_branch .LBB0_449
